# MLA loop: K chunk-1 fragment reads behind the first MFMA, V fragment reads behind K chunk 2 (bench: -3.4% loop cycles)
# baseline (speedup 1.0000x reference)
; #define LAS __attribute__((address_space(3)))
; template <int DQK, int DV, int FLAGS, int qp, int kp, int vts, int op> ...
;     ...
; #pragma unroll
;             for (int c = 0; c < ND0 / 2; ++c) {
;                 if (c + 1 < ND0 / 2) {
; #pragma unroll
;                     for (int i = 0; i < 2; ++i) { kf[(c + 1) & 1][2 * i] = *(const LAS bf16x8*)(kb + (2 * c + 2 + i) * 32); kf[(c + 1) & 1][2 * i + 1] = *(const LAS bf16x8*)(kb + 32 * KROW + (2 * c + 2 + i) * 32); }
;                 }
; #pragma unroll
;                 for (int i = 0; i < 2; ++i) {
;                     p0 = __builtin_amdgcn_mfma_f32_32x32x16_bf16(kf[c & 1][2 * i], qr[2 * c + i], p0, 0, 0, 0);
;                     p1 = __builtin_amdgcn_mfma_f32_32x32x16_bf16(kf[c & 1][2 * i + 1], qr[2 * c + i], p1, 0, 0, 0);
;                 }
;                 __builtin_amdgcn_sched_barrier(0);
;             }
;             if (more) ATT_GLOAD((FLAGS & AF_REV) ? t - 1 : t + 1);
;             bf16x8 vf[2][4];
; #pragma unroll
;             for (int ks = 0; ks < 4; ++ks) vf[0][ks] = *(const LAS bf16x8*)(vb + ks * 32);
;     ...
;             f32x2 rs2 = {0.f, 0.f};
; #pragma unroll
;             for (int r = 0; r < 16; ++r) { p0[r] = __builtin_amdgcn_exp2f(p0[r]); p1[r] = __builtin_amdgcn_exp2f(p1[r]); }
; #pragma unroll
;             for (int r = 0; r < 16; r += 2) { rs2 += (f32x2){p0[r], p0[r + 1]}; rs2 += (f32x2){p1[r], p1[r + 1]}; }
;             l += rs2.x + rs2.y;
;             bf16x8 pf[4];
;             pf[0] = pack_bf16x8(p0, 0); pf[1] = pack_bf16x8(p0, 8); pf[2] = pack_bf16x8(p1, 0); pf[3] = pack_bf16x8(p1, 8);
;             __builtin_amdgcn_sched_barrier(0);
; #pragma unroll
;             for (int d = 0; d < NDB; ++d) {
;                 if (d + 1 < NDB) {
; #pragma unroll
;                     for (int ks = 0; ks < 4; ++ks) vf[(d + 1) & 1][ks] = *(const LAS bf16x8*)(vb + (d + 1) * 32 * VROW + ks * 32);
;                 }
; #pragma unroll
;                 for (int ks = 0; ks < 4; ++ks) o[d] = __builtin_amdgcn_mfma_f32_32x32x16_bf16(vf[d & 1][ks], pf[ks], o[d], 0, 0, 0);
;                 __builtin_amdgcn_sched_barrier(0);
;             }
.Lq_top0:
	s_cmp_eq_u32 s3, 0
	s_cbranch_scc1 .Lq_gen0
	s_add_i32 s13, s3, 1
	s_cmp_ge_i32 s13, s20
	s_cbranch_scc1 .Lq_gen0
	ds_read_b128 v[96:99], v187 offset:22528
	ds_read_b128 v[104:107], v187 offset:29184
	ds_read_b128 v[100:103], v187 offset:22560
	ds_read_b128 v[108:111], v187 offset:29216
	v_mfma_f32_32x32x16_bf16 v[32:47], v[152:155], v[214:217], v[32:47]
	v_exp_f32_e32 v64, v64
	v_exp_f32_e32 v65, v65
	ds_read_b128 v[112:115], v187 offset:22592
	ds_read_b128 v[120:123], v187 offset:29248
	ds_read_b128 v[116:119], v187 offset:22624
	ds_read_b128 v[124:127], v187 offset:29280
	v_mfma_f32_32x32x16_bf16 v[16:31], v[188:191], v[214:217], v[16:31]
	v_exp_f32_e32 v80, v80
	v_exp_f32_e32 v81, v81
	v_add_f32_e32 v204, v64, v175
	s_waitcnt vmcnt(0)
	ds_write_b128 v248, v[140:143] offset:0
	v_mfma_f32_32x32x16_bf16 v[32:47], v[156:159], v[218:221], v[32:47]
	v_exp_f32_e32 v66, v66
	v_exp_f32_e32 v67, v67
	v_add_f32_e32 v204, v80, v204
	v_add_f32_e32 v205, v65, v81
	ds_write_b128 v249, v[148:151] offset:13312
	v_mfma_f32_32x32x16_bf16 v[16:31], v[192:195], v[218:221], v[16:31]
	v_exp_f32_e32 v82, v82
	v_exp_f32_e32 v83, v83
	v_add_f32_e32 v204, v66, v204
	v_add_f32_e32 v205, v67, v205
	s_and_saveexec_b64 s[14:15], s[10:11]
	ds_write_b128 v250, v[144:147] offset:0
	s_or_b64 exec, exec, s[14:15]
	v_mfma_f32_32x32x16_bf16 v[32:47], v[160:163], v[222:225], v[32:47]
	v_exp_f32_e32 v68, v68
	v_exp_f32_e32 v69, v69
	v_add_f32_e32 v204, v82, v204
	v_add_f32_e32 v205, v83, v205
	s_add_i32 s12, s3, 3
	s_cmp_ge_i32 s12, s2
	s_cbranch_scc1 .Lq_ng0_s0
	s_and_saveexec_b64 s[14:15], s[10:11]
	global_load_dwordx4 v[144:147], v180, s[98:99]
	s_or_b64 exec, exec, s[14:15]

; #define LAS __attribute__((address_space(3)))
; template <int DQK, int DV, int FLAGS, int qp, int kp, int vts, int op> ...
;     ...
; #pragma unroll
;             for (int c = 0; c < ND0 / 2; ++c) {
;                 if (c + 1 < ND0 / 2) {
; #pragma unroll
;                     for (int i = 0; i < 2; ++i) { kf[(c + 1) & 1][2 * i] = *(const LAS bf16x8*)(kb + (2 * c + 2 + i) * 32); kf[(c + 1) & 1][2 * i + 1] = *(const LAS bf16x8*)(kb + 32 * KROW + (2 * c + 2 + i) * 32); }
;                 }
; #pragma unroll
;                 for (int i = 0; i < 2; ++i) {
;                     p0 = __builtin_amdgcn_mfma_f32_32x32x16_bf16(kf[c & 1][2 * i], qr[2 * c + i], p0, 0, 0, 0);
;                     p1 = __builtin_amdgcn_mfma_f32_32x32x16_bf16(kf[c & 1][2 * i + 1], qr[2 * c + i], p1, 0, 0, 0);
;                 }
;                 __builtin_amdgcn_sched_barrier(0);
;             }
;             if (more) ATT_GLOAD((FLAGS & AF_REV) ? t - 1 : t + 1);
;             bf16x8 vf[2][4];
; #pragma unroll
;             for (int ks = 0; ks < 4; ++ks) vf[0][ks] = *(const LAS bf16x8*)(vb + ks * 32);
;     ...
;             f32x2 rs2 = {0.f, 0.f};
; #pragma unroll
;             for (int r = 0; r < 16; ++r) { p0[r] = __builtin_amdgcn_exp2f(p0[r]); p1[r] = __builtin_amdgcn_exp2f(p1[r]); }
; #pragma unroll
;             for (int r = 0; r < 16; r += 2) { rs2 += (f32x2){p0[r], p0[r + 1]}; rs2 += (f32x2){p1[r], p1[r + 1]}; }
;             l += rs2.x + rs2.y;
;             bf16x8 pf[4];
;             pf[0] = pack_bf16x8(p0, 0); pf[1] = pack_bf16x8(p0, 8); pf[2] = pack_bf16x8(p1, 0); pf[3] = pack_bf16x8(p1, 8);
;             __builtin_amdgcn_sched_barrier(0);
; #pragma unroll
;             for (int d = 0; d < NDB; ++d) {
;                 if (d + 1 < NDB) {
; #pragma unroll
;                     for (int ks = 0; ks < 4; ++ks) vf[(d + 1) & 1][ks] = *(const LAS bf16x8*)(vb + (d + 1) * 32 * VROW + ks * 32);
;                 }
; #pragma unroll
;                 for (int ks = 0; ks < 4; ++ks) o[d] = __builtin_amdgcn_mfma_f32_32x32x16_bf16(vf[d & 1][ks], pf[ks], o[d], 0, 0, 0);
;                 __builtin_amdgcn_sched_barrier(0);
;             }
.Lq_ng2_s0:
	v_mfma_f32_32x32x16_bf16 v[16:31], v[200:203], v[226:229], v[16:31]
	v_exp_f32_e32 v86, v86
	v_exp_f32_e32 v87, v87
	v_add_f32_e32 v204, v70, v204
	v_add_f32_e32 v205, v71, v205
	s_waitcnt lgkmcnt(6)
	v_mfma_f32_32x32x16_bf16 v[214:229], v[96:99], v[2:5], v[48:63]
	v_exp_f32_e32 v72, v72
	v_exp_f32_e32 v73, v73
	v_add_f32_e32 v204, v86, v204
	v_add_f32_e32 v205, v87, v205
	v_mfma_f32_32x32x16_bf16 v[230:245], v[104:107], v[2:5], v[48:63]
	v_exp_f32_e32 v88, v88
	v_exp_f32_e32 v89, v89
	v_add_f32_e32 v204, v72, v204
	v_add_f32_e32 v205, v73, v205
	v_mfma_f32_32x32x16_bf16 v[214:229], v[100:103], v[6:9], v[214:229]
	v_exp_f32_e32 v74, v74
	v_exp_f32_e32 v75, v75
	v_add_f32_e32 v204, v88, v204
	v_add_f32_e32 v205, v89, v205
	v_mfma_f32_32x32x16_bf16 v[230:245], v[108:111], v[6:9], v[230:245]
	v_exp_f32_e32 v90, v90
	v_exp_f32_e32 v91, v91
	v_add_f32_e32 v204, v74, v204
	v_add_f32_e32 v205, v75, v205
	ds_read_b128 v[96:99], v187 offset:22656
	ds_read_b128 v[104:107], v187 offset:29312
	ds_read_b128 v[100:103], v187 offset:22688
	ds_read_b128 v[108:111], v187 offset:29344
	s_waitcnt lgkmcnt(6)
	v_mfma_f32_32x32x16_bf16 v[214:229], v[112:115], v[10:13], v[214:229]
	v_exp_f32_e32 v76, v76
	v_exp_f32_e32 v77, v77
	v_add_f32_e32 v204, v90, v204
	v_add_f32_e32 v205, v91, v205
	v_mfma_f32_32x32x16_bf16 v[230:245], v[120:123], v[10:13], v[230:245]
	v_exp_f32_e32 v92, v92
	v_exp_f32_e32 v93, v93
	v_add_f32_e32 v204, v76, v204
	v_add_f32_e32 v205, v77, v205
	ds_read_b128 v[152:155], v246 offset:13312
	ds_read_b128 v[156:159], v246 offset:13344
	ds_read_b128 v[160:163], v246 offset:13376
	ds_read_b128 v[164:167], v246 offset:13408
	v_mfma_f32_32x32x16_bf16 v[214:229], v[116:119], v[128:131], v[214:229]
	v_exp_f32_e32 v78, v78
	v_exp_f32_e32 v79, v79
	v_add_f32_e32 v204, v92, v204
	v_add_f32_e32 v205, v93, v205
	v_mfma_f32_32x32x16_bf16 v[230:245], v[124:127], v[128:131], v[230:245]
	v_exp_f32_e32 v94, v94
	v_exp_f32_e32 v95, v95
	v_add_f32_e32 v204, v78, v204
	v_add_f32_e32 v205, v79, v205
	ds_read_b128 v[188:191], v246 offset:17920
	ds_read_b128 v[192:195], v246 offset:17952
	ds_read_b128 v[196:199], v246 offset:17984
	ds_read_b128 v[200:203], v246 offset:18016
	s_waitcnt lgkmcnt(8)
	v_mfma_f32_32x32x16_bf16 v[214:229], v[96:99], v[132:135], v[214:229]
	v_add_f32_e32 v204, v94, v204
	v_add_f32_e32 v205, v95, v205
	v_cvt_pk_bf16_f32 v64, v64, v65
	v_cvt_pk_bf16_f32 v65, v66, v67
	v_cvt_pk_bf16_f32 v66, v68, v69
	v_mfma_f32_32x32x16_bf16 v[230:245], v[104:107], v[132:135], v[230:245]
	v_cvt_pk_bf16_f32 v67, v70, v71
	v_cvt_pk_bf16_f32 v68, v72, v73
	v_cvt_pk_bf16_f32 v69, v74, v75
	v_cvt_pk_bf16_f32 v70, v76, v77
	v_cvt_pk_bf16_f32 v71, v78, v79
	v_mfma_f32_32x32x16_bf16 v[214:229], v[100:103], v[136:139], v[214:229]
	v_cvt_pk_bf16_f32 v72, v80, v81
	v_cvt_pk_bf16_f32 v73, v82, v83
	v_cvt_pk_bf16_f32 v74, v84, v85
	v_cvt_pk_bf16_f32 v75, v86, v87
	v_cvt_pk_bf16_f32 v76, v88, v89
	v_mfma_f32_32x32x16_bf16 v[230:245], v[108:111], v[136:139], v[230:245]
	v_cvt_pk_bf16_f32 v77, v90, v91
	v_cvt_pk_bf16_f32 v78, v92, v93
	v_cvt_pk_bf16_f32 v79, v94, v95
	v_add_f32_e32 v175, v204, v205
	s_branch .Lq_tailb0

; template <int DQK, int DV, int FLAGS, int qp, int kp, int vts, int op> ...
;     ...
;             f32x2 rs2 = {0.f, 0.f};
; #pragma unroll
;             for (int r = 0; r < 16; ++r) { p0[r] = __builtin_amdgcn_exp2f(p0[r]); p1[r] = __builtin_amdgcn_exp2f(p1[r]); }
; #pragma unroll
;             for (int r = 0; r < 16; r += 2) { rs2 += (f32x2){p0[r], p0[r + 1]}; rs2 += (f32x2){p1[r], p1[r + 1]}; }
;             l += rs2.x + rs2.y;
;             bf16x8 pf[4];
;             pf[0] = pack_bf16x8(p0, 0); pf[1] = pack_bf16x8(p0, 8); pf[2] = pack_bf16x8(p1, 0); pf[3] = pack_bf16x8(p1, 8);
.Lq_notfirst_q0:
	v_exp_f32_e32 v64, v64
	v_exp_f32_e32 v65, v65
	v_exp_f32_e32 v80, v80
	v_exp_f32_e32 v81, v81
	v_add_f32_e32 v204, v64, v175
	v_exp_f32_e32 v66, v66
	v_exp_f32_e32 v67, v67
	v_add_f32_e32 v204, v80, v204
	v_add_f32_e32 v205, v65, v81
	v_exp_f32_e32 v82, v82
	v_exp_f32_e32 v83, v83
	v_add_f32_e32 v204, v66, v204
	v_add_f32_e32 v205, v67, v205
	v_exp_f32_e32 v68, v68
	v_exp_f32_e32 v69, v69
	v_add_f32_e32 v204, v82, v204
	v_add_f32_e32 v205, v83, v205
	v_exp_f32_e32 v84, v84
	v_exp_f32_e32 v85, v85
	v_add_f32_e32 v204, v68, v204
	v_add_f32_e32 v205, v69, v205
	v_exp_f32_e32 v70, v70
	v_exp_f32_e32 v71, v71
	v_add_f32_e32 v204, v84, v204
	v_add_f32_e32 v205, v85, v205
	v_exp_f32_e32 v86, v86
	v_exp_f32_e32 v87, v87
	v_add_f32_e32 v204, v70, v204
	v_add_f32_e32 v205, v71, v205
	v_exp_f32_e32 v72, v72
	v_exp_f32_e32 v73, v73
	v_add_f32_e32 v204, v86, v204
	v_add_f32_e32 v205, v87, v205
	v_exp_f32_e32 v88, v88
	v_exp_f32_e32 v89, v89
	v_add_f32_e32 v204, v72, v204
	v_add_f32_e32 v205, v73, v205
	v_exp_f32_e32 v74, v74
	v_exp_f32_e32 v75, v75
	v_add_f32_e32 v204, v88, v204
	v_add_f32_e32 v205, v89, v205
	v_exp_f32_e32 v90, v90
	v_exp_f32_e32 v91, v91
	v_add_f32_e32 v204, v74, v204
	v_add_f32_e32 v205, v75, v205
	v_exp_f32_e32 v76, v76
	v_exp_f32_e32 v77, v77
	v_add_f32_e32 v204, v90, v204
	v_add_f32_e32 v205, v91, v205
	v_exp_f32_e32 v92, v92
	v_exp_f32_e32 v93, v93
	v_add_f32_e32 v204, v76, v204
	v_add_f32_e32 v205, v77, v205
	v_exp_f32_e32 v78, v78
	v_exp_f32_e32 v79, v79
	v_add_f32_e32 v204, v92, v204
	v_add_f32_e32 v205, v93, v205
	v_exp_f32_e32 v94, v94
	v_exp_f32_e32 v95, v95
	v_add_f32_e32 v204, v78, v204
	v_add_f32_e32 v205, v79, v205
	v_add_f32_e32 v204, v94, v204
	v_add_f32_e32 v205, v95, v205
	v_cvt_pk_bf16_f32 v64, v64, v65
	v_cvt_pk_bf16_f32 v65, v66, v67
	v_cvt_pk_bf16_f32 v66, v68, v69
	v_cvt_pk_bf16_f32 v67, v70, v71
	v_cvt_pk_bf16_f32 v68, v72, v73
	v_cvt_pk_bf16_f32 v69, v74, v75
	v_cvt_pk_bf16_f32 v70, v76, v77
	v_cvt_pk_bf16_f32 v71, v78, v79
	v_cvt_pk_bf16_f32 v72, v80, v81
	v_cvt_pk_bf16_f32 v73, v82, v83
	v_cvt_pk_bf16_f32 v74, v84, v85
	v_cvt_pk_bf16_f32 v75, v86, v87
	v_cvt_pk_bf16_f32 v76, v88, v89
	v_cvt_pk_bf16_f32 v77, v90, v91
	v_cvt_pk_bf16_f32 v78, v92, v93
	v_cvt_pk_bf16_f32 v79, v94, v95
	v_add_f32_e32 v175, v204, v205

; #define LAS __attribute__((address_space(3)))
; template <int DQK, int DV, int FLAGS, int qp, int kp, int vts, int op> ...
;     ...
; #pragma unroll
;             for (int c = 0; c < ND0 / 2; ++c) {
;                 if (c + 1 < ND0 / 2) {
; #pragma unroll
;                     for (int i = 0; i < 2; ++i) { kf[(c + 1) & 1][2 * i] = *(const LAS bf16x8*)(kb + (2 * c + 2 + i) * 32); kf[(c + 1) & 1][2 * i + 1] = *(const LAS bf16x8*)(kb + 32 * KROW + (2 * c + 2 + i) * 32); }
;                 }
; #pragma unroll
;                 for (int i = 0; i < 2; ++i) {
;                     p0 = __builtin_amdgcn_mfma_f32_32x32x16_bf16(kf[c & 1][2 * i], qr[2 * c + i], p0, 0, 0, 0);
;                     p1 = __builtin_amdgcn_mfma_f32_32x32x16_bf16(kf[c & 1][2 * i + 1], qr[2 * c + i], p1, 0, 0, 0);
;                 }
;                 __builtin_amdgcn_sched_barrier(0);
;             }
;             if (more) ATT_GLOAD((FLAGS & AF_REV) ? t - 1 : t + 1);
;             bf16x8 vf[2][4];
; #pragma unroll
;             for (int ks = 0; ks < 4; ++ks) vf[0][ks] = *(const LAS bf16x8*)(vb + ks * 32);
;     ...
;             f32x2 rs2 = {0.f, 0.f};
; #pragma unroll
;             for (int r = 0; r < 16; ++r) { p0[r] = __builtin_amdgcn_exp2f(p0[r]); p1[r] = __builtin_amdgcn_exp2f(p1[r]); }
; #pragma unroll
;             for (int r = 0; r < 16; r += 2) { rs2 += (f32x2){p0[r], p0[r + 1]}; rs2 += (f32x2){p1[r], p1[r + 1]}; }
;             l += rs2.x + rs2.y;
;             bf16x8 pf[4];
;             pf[0] = pack_bf16x8(p0, 0); pf[1] = pack_bf16x8(p0, 8); pf[2] = pack_bf16x8(p1, 0); pf[3] = pack_bf16x8(p1, 8);
;             __builtin_amdgcn_sched_barrier(0);
; #pragma unroll
;             for (int d = 0; d < NDB; ++d) {
;                 if (d + 1 < NDB) {
; #pragma unroll
;                     for (int ks = 0; ks < 4; ++ks) vf[(d + 1) & 1][ks] = *(const LAS bf16x8*)(vb + (d + 1) * 32 * VROW + ks * 32);
;                 }
; #pragma unroll
;                 for (int ks = 0; ks < 4; ++ks) o[d] = __builtin_amdgcn_mfma_f32_32x32x16_bf16(vf[d & 1][ks], pf[ks], o[d], 0, 0, 0);
;                 __builtin_amdgcn_sched_barrier(0);
;             }
.Lq_top1:
	s_cmp_eq_u32 s3, 0
	s_cbranch_scc1 .Lq_gen1
	s_add_i32 s13, s3, 1
	s_cmp_ge_i32 s13, s20
	s_cbranch_scc1 .Lq_gen1
	ds_read_b128 v[96:99], v213 offset:0
	ds_read_b128 v[104:107], v213 offset:6656
	ds_read_b128 v[100:103], v213 offset:32
	ds_read_b128 v[108:111], v213 offset:6688
	v_mfma_f32_32x32x16_bf16 v[32:47], v[152:155], v[64:67], v[32:47]
	v_exp_f32_e32 v214, v214
	v_exp_f32_e32 v215, v215
	ds_read_b128 v[112:115], v213 offset:64
	ds_read_b128 v[120:123], v213 offset:6720
	ds_read_b128 v[116:119], v213 offset:96
	ds_read_b128 v[124:127], v213 offset:6752
	v_mfma_f32_32x32x16_bf16 v[16:31], v[188:191], v[64:67], v[16:31]
	v_exp_f32_e32 v230, v230
	v_exp_f32_e32 v231, v231
	v_add_f32_e32 v204, v214, v175
	s_waitcnt vmcnt(0)
	ds_write_b128 v248, v[140:143] offset:22528
	v_mfma_f32_32x32x16_bf16 v[32:47], v[156:159], v[68:71], v[32:47]
	v_exp_f32_e32 v216, v216
	v_exp_f32_e32 v217, v217
	v_add_f32_e32 v204, v230, v204
	v_add_f32_e32 v205, v215, v231
	ds_write_b128 v249, v[148:151] offset:35840
	v_mfma_f32_32x32x16_bf16 v[16:31], v[192:195], v[68:71], v[16:31]
	v_exp_f32_e32 v232, v232
	v_exp_f32_e32 v233, v233
	v_add_f32_e32 v204, v216, v204
	v_add_f32_e32 v205, v217, v205
	s_and_saveexec_b64 s[14:15], s[10:11]
	ds_write_b128 v250, v[144:147] offset:22528
	s_or_b64 exec, exec, s[14:15]
	v_mfma_f32_32x32x16_bf16 v[32:47], v[160:163], v[72:75], v[32:47]
	v_exp_f32_e32 v218, v218
	v_exp_f32_e32 v219, v219
	v_add_f32_e32 v204, v232, v204
	v_add_f32_e32 v205, v233, v205
	s_add_i32 s12, s3, 3
	s_cmp_ge_i32 s12, s2
	s_cbranch_scc1 .Lq_ng0_s1
	s_and_saveexec_b64 s[14:15], s[10:11]
	global_load_dwordx4 v[144:147], v180, s[98:99]
	s_or_b64 exec, exec, s[14:15]

; #define LAS __attribute__((address_space(3)))
; template <int DQK, int DV, int FLAGS, int qp, int kp, int vts, int op> ...
;     ...
; #pragma unroll
;             for (int c = 0; c < ND0 / 2; ++c) {
;                 if (c + 1 < ND0 / 2) {
; #pragma unroll
;                     for (int i = 0; i < 2; ++i) { kf[(c + 1) & 1][2 * i] = *(const LAS bf16x8*)(kb + (2 * c + 2 + i) * 32); kf[(c + 1) & 1][2 * i + 1] = *(const LAS bf16x8*)(kb + 32 * KROW + (2 * c + 2 + i) * 32); }
;                 }
; #pragma unroll
;                 for (int i = 0; i < 2; ++i) {
;                     p0 = __builtin_amdgcn_mfma_f32_32x32x16_bf16(kf[c & 1][2 * i], qr[2 * c + i], p0, 0, 0, 0);
;                     p1 = __builtin_amdgcn_mfma_f32_32x32x16_bf16(kf[c & 1][2 * i + 1], qr[2 * c + i], p1, 0, 0, 0);
;                 }
;                 __builtin_amdgcn_sched_barrier(0);
;             }
;             if (more) ATT_GLOAD((FLAGS & AF_REV) ? t - 1 : t + 1);
;             bf16x8 vf[2][4];
; #pragma unroll
;             for (int ks = 0; ks < 4; ++ks) vf[0][ks] = *(const LAS bf16x8*)(vb + ks * 32);
;     ...
;             f32x2 rs2 = {0.f, 0.f};
; #pragma unroll
;             for (int r = 0; r < 16; ++r) { p0[r] = __builtin_amdgcn_exp2f(p0[r]); p1[r] = __builtin_amdgcn_exp2f(p1[r]); }
; #pragma unroll
;             for (int r = 0; r < 16; r += 2) { rs2 += (f32x2){p0[r], p0[r + 1]}; rs2 += (f32x2){p1[r], p1[r + 1]}; }
;             l += rs2.x + rs2.y;
;             bf16x8 pf[4];
;             pf[0] = pack_bf16x8(p0, 0); pf[1] = pack_bf16x8(p0, 8); pf[2] = pack_bf16x8(p1, 0); pf[3] = pack_bf16x8(p1, 8);
;             __builtin_amdgcn_sched_barrier(0);
; #pragma unroll
;             for (int d = 0; d < NDB; ++d) {
;                 if (d + 1 < NDB) {
; #pragma unroll
;                     for (int ks = 0; ks < 4; ++ks) vf[(d + 1) & 1][ks] = *(const LAS bf16x8*)(vb + (d + 1) * 32 * VROW + ks * 32);
;                 }
; #pragma unroll
;                 for (int ks = 0; ks < 4; ++ks) o[d] = __builtin_amdgcn_mfma_f32_32x32x16_bf16(vf[d & 1][ks], pf[ks], o[d], 0, 0, 0);
;                 __builtin_amdgcn_sched_barrier(0);
;             }
.Lq_ng2_s1:
	v_mfma_f32_32x32x16_bf16 v[16:31], v[200:203], v[76:79], v[16:31]
	v_exp_f32_e32 v236, v236
	v_exp_f32_e32 v237, v237
	v_add_f32_e32 v204, v220, v204
	v_add_f32_e32 v205, v221, v205
	s_waitcnt lgkmcnt(6)
	v_mfma_f32_32x32x16_bf16 v[64:79], v[96:99], v[2:5], v[48:63]
	v_exp_f32_e32 v222, v222
	v_exp_f32_e32 v223, v223
	v_add_f32_e32 v204, v236, v204
	v_add_f32_e32 v205, v237, v205
	v_mfma_f32_32x32x16_bf16 v[80:95], v[104:107], v[2:5], v[48:63]
	v_exp_f32_e32 v238, v238
	v_exp_f32_e32 v239, v239
	v_add_f32_e32 v204, v222, v204
	v_add_f32_e32 v205, v223, v205
	v_mfma_f32_32x32x16_bf16 v[64:79], v[100:103], v[6:9], v[64:79]
	v_exp_f32_e32 v224, v224
	v_exp_f32_e32 v225, v225
	v_add_f32_e32 v204, v238, v204
	v_add_f32_e32 v205, v239, v205
	v_mfma_f32_32x32x16_bf16 v[80:95], v[108:111], v[6:9], v[80:95]
	v_exp_f32_e32 v240, v240
	v_exp_f32_e32 v241, v241
	v_add_f32_e32 v204, v224, v204
	v_add_f32_e32 v205, v225, v205
	ds_read_b128 v[96:99], v213 offset:128
	ds_read_b128 v[104:107], v213 offset:6784
	ds_read_b128 v[100:103], v213 offset:160
	ds_read_b128 v[108:111], v213 offset:6816
	s_waitcnt lgkmcnt(6)
	v_mfma_f32_32x32x16_bf16 v[64:79], v[112:115], v[10:13], v[64:79]
	v_exp_f32_e32 v226, v226
	v_exp_f32_e32 v227, v227
	v_add_f32_e32 v204, v240, v204
	v_add_f32_e32 v205, v241, v205
	v_mfma_f32_32x32x16_bf16 v[80:95], v[120:123], v[10:13], v[80:95]
	v_exp_f32_e32 v242, v242
	v_exp_f32_e32 v243, v243
	v_add_f32_e32 v204, v226, v204
	v_add_f32_e32 v205, v227, v205
	ds_read_b128 v[152:155], v246 offset:35840
	ds_read_b128 v[156:159], v246 offset:35872
	ds_read_b128 v[160:163], v246 offset:35904
	ds_read_b128 v[164:167], v246 offset:35936
	v_mfma_f32_32x32x16_bf16 v[64:79], v[116:119], v[128:131], v[64:79]
	v_exp_f32_e32 v228, v228
	v_exp_f32_e32 v229, v229
	v_add_f32_e32 v204, v242, v204
	v_add_f32_e32 v205, v243, v205
	v_mfma_f32_32x32x16_bf16 v[80:95], v[124:127], v[128:131], v[80:95]
	v_exp_f32_e32 v244, v244
	v_exp_f32_e32 v245, v245
	v_add_f32_e32 v204, v228, v204
	v_add_f32_e32 v205, v229, v205
	ds_read_b128 v[188:191], v246 offset:40448
	ds_read_b128 v[192:195], v246 offset:40480
	ds_read_b128 v[196:199], v246 offset:40512
	ds_read_b128 v[200:203], v246 offset:40544
	s_waitcnt lgkmcnt(8)
	v_mfma_f32_32x32x16_bf16 v[64:79], v[96:99], v[132:135], v[64:79]
	v_add_f32_e32 v204, v244, v204
	v_add_f32_e32 v205, v245, v205
	v_cvt_pk_bf16_f32 v214, v214, v215
	v_cvt_pk_bf16_f32 v215, v216, v217
	v_cvt_pk_bf16_f32 v216, v218, v219
	v_mfma_f32_32x32x16_bf16 v[80:95], v[104:107], v[132:135], v[80:95]
	v_cvt_pk_bf16_f32 v217, v220, v221
	v_cvt_pk_bf16_f32 v218, v222, v223
	v_cvt_pk_bf16_f32 v219, v224, v225
	v_cvt_pk_bf16_f32 v220, v226, v227
	v_cvt_pk_bf16_f32 v221, v228, v229
	v_mfma_f32_32x32x16_bf16 v[64:79], v[100:103], v[136:139], v[64:79]
	v_cvt_pk_bf16_f32 v222, v230, v231
	v_cvt_pk_bf16_f32 v223, v232, v233
	v_cvt_pk_bf16_f32 v224, v234, v235
	v_cvt_pk_bf16_f32 v225, v236, v237
	v_cvt_pk_bf16_f32 v226, v238, v239
	v_mfma_f32_32x32x16_bf16 v[80:95], v[108:111], v[136:139], v[80:95]
	v_cvt_pk_bf16_f32 v227, v240, v241
	v_cvt_pk_bf16_f32 v228, v242, v243
	v_cvt_pk_bf16_f32 v229, v244, v245
	v_add_f32_e32 v175, v204, v205
	s_branch .Lq_tailb1

; template <int DQK, int DV, int FLAGS, int qp, int kp, int vts, int op> ...
;     ...
;             f32x2 rs2 = {0.f, 0.f};
; #pragma unroll
;             for (int r = 0; r < 16; ++r) { p0[r] = __builtin_amdgcn_exp2f(p0[r]); p1[r] = __builtin_amdgcn_exp2f(p1[r]); }
; #pragma unroll
;             for (int r = 0; r < 16; r += 2) { rs2 += (f32x2){p0[r], p0[r + 1]}; rs2 += (f32x2){p1[r], p1[r + 1]}; }
;             l += rs2.x + rs2.y;
;             bf16x8 pf[4];
;             pf[0] = pack_bf16x8(p0, 0); pf[1] = pack_bf16x8(p0, 8); pf[2] = pack_bf16x8(p1, 0); pf[3] = pack_bf16x8(p1, 8);
.Lq_notfirst_q1:
	v_exp_f32_e32 v214, v214
	v_exp_f32_e32 v215, v215
	v_exp_f32_e32 v230, v230
	v_exp_f32_e32 v231, v231
	v_add_f32_e32 v204, v214, v175
	v_exp_f32_e32 v216, v216
	v_exp_f32_e32 v217, v217
	v_add_f32_e32 v204, v230, v204
	v_add_f32_e32 v205, v215, v231
	v_exp_f32_e32 v232, v232
	v_exp_f32_e32 v233, v233
	v_add_f32_e32 v204, v216, v204
	v_add_f32_e32 v205, v217, v205
	v_exp_f32_e32 v218, v218
	v_exp_f32_e32 v219, v219
	v_add_f32_e32 v204, v232, v204
	v_add_f32_e32 v205, v233, v205
	v_exp_f32_e32 v234, v234
	v_exp_f32_e32 v235, v235
	v_add_f32_e32 v204, v218, v204
	v_add_f32_e32 v205, v219, v205
	v_exp_f32_e32 v220, v220
	v_exp_f32_e32 v221, v221
	v_add_f32_e32 v204, v234, v204
	v_add_f32_e32 v205, v235, v205
	v_exp_f32_e32 v236, v236
	v_exp_f32_e32 v237, v237
	v_add_f32_e32 v204, v220, v204
	v_add_f32_e32 v205, v221, v205
	v_exp_f32_e32 v222, v222
	v_exp_f32_e32 v223, v223
	v_add_f32_e32 v204, v236, v204
	v_add_f32_e32 v205, v237, v205
	v_exp_f32_e32 v238, v238
	v_exp_f32_e32 v239, v239
	v_add_f32_e32 v204, v222, v204
	v_add_f32_e32 v205, v223, v205
	v_exp_f32_e32 v224, v224
	v_exp_f32_e32 v225, v225
	v_add_f32_e32 v204, v238, v204
	v_add_f32_e32 v205, v239, v205
	v_exp_f32_e32 v240, v240
	v_exp_f32_e32 v241, v241
	v_add_f32_e32 v204, v224, v204
	v_add_f32_e32 v205, v225, v205
	v_exp_f32_e32 v226, v226
	v_exp_f32_e32 v227, v227
	v_add_f32_e32 v204, v240, v204
	v_add_f32_e32 v205, v241, v205
	v_exp_f32_e32 v242, v242
	v_exp_f32_e32 v243, v243
	v_add_f32_e32 v204, v226, v204
	v_add_f32_e32 v205, v227, v205
	v_exp_f32_e32 v228, v228
	v_exp_f32_e32 v229, v229
	v_add_f32_e32 v204, v242, v204
	v_add_f32_e32 v205, v243, v205
	v_exp_f32_e32 v244, v244
	v_exp_f32_e32 v245, v245
	v_add_f32_e32 v204, v228, v204
	v_add_f32_e32 v205, v229, v205
	v_add_f32_e32 v204, v244, v204
	v_add_f32_e32 v205, v245, v205
	v_cvt_pk_bf16_f32 v214, v214, v215
	v_cvt_pk_bf16_f32 v215, v216, v217
	v_cvt_pk_bf16_f32 v216, v218, v219
	v_cvt_pk_bf16_f32 v217, v220, v221
	v_cvt_pk_bf16_f32 v218, v222, v223
	v_cvt_pk_bf16_f32 v219, v224, v225
	v_cvt_pk_bf16_f32 v220, v226, v227
	v_cvt_pk_bf16_f32 v221, v228, v229
	v_cvt_pk_bf16_f32 v222, v230, v231
	v_cvt_pk_bf16_f32 v223, v232, v233
	v_cvt_pk_bf16_f32 v224, v234, v235
	v_cvt_pk_bf16_f32 v225, v236, v237
	v_cvt_pk_bf16_f32 v226, v238, v239
	v_cvt_pk_bf16_f32 v227, v240, v241
	v_cvt_pk_bf16_f32 v228, v242, v243
	v_cvt_pk_bf16_f32 v229, v244, v245
	v_add_f32_e32 v175, v204, v205

; #define LAS __attribute__((address_space(3)))
; template <int DQK, int DV, int FLAGS, int qp, int kp, int vts, int op> ...
;     ...
; #pragma unroll
;             for (int c = 0; c < ND0 / 2; ++c) {
;                 if (c + 1 < ND0 / 2) {
; #pragma unroll
;                     for (int i = 0; i < 2; ++i) { kf[(c + 1) & 1][2 * i] = *(const LAS bf16x8*)(kb + (2 * c + 2 + i) * 32); kf[(c + 1) & 1][2 * i + 1] = *(const LAS bf16x8*)(kb + 32 * KROW + (2 * c + 2 + i) * 32); }
;                 }
; #pragma unroll
;                 for (int i = 0; i < 2; ++i) {
;                     p0 = __builtin_amdgcn_mfma_f32_32x32x16_bf16(kf[c & 1][2 * i], qr[2 * c + i], p0, 0, 0, 0);
;                     p1 = __builtin_amdgcn_mfma_f32_32x32x16_bf16(kf[c & 1][2 * i + 1], qr[2 * c + i], p1, 0, 0, 0);
;                 }
;                 __builtin_amdgcn_sched_barrier(0);
;             }
;             if (more) ATT_GLOAD((FLAGS & AF_REV) ? t - 1 : t + 1);
;             bf16x8 vf[2][4];
; #pragma unroll
;             for (int ks = 0; ks < 4; ++ks) vf[0][ks] = *(const LAS bf16x8*)(vb + ks * 32);
;     ...
;             f32x2 rs2 = {0.f, 0.f};
; #pragma unroll
;             for (int r = 0; r < 16; ++r) { p0[r] = __builtin_amdgcn_exp2f(p0[r]); p1[r] = __builtin_amdgcn_exp2f(p1[r]); }
; #pragma unroll
;             for (int r = 0; r < 16; r += 2) { rs2 += (f32x2){p0[r], p0[r + 1]}; rs2 += (f32x2){p1[r], p1[r + 1]}; }
;             l += rs2.x + rs2.y;
;             bf16x8 pf[4];
;             pf[0] = pack_bf16x8(p0, 0); pf[1] = pack_bf16x8(p0, 8); pf[2] = pack_bf16x8(p1, 0); pf[3] = pack_bf16x8(p1, 8);
;             __builtin_amdgcn_sched_barrier(0);
; #pragma unroll
;             for (int d = 0; d < NDB; ++d) {
;                 if (d + 1 < NDB) {
; #pragma unroll
;                     for (int ks = 0; ks < 4; ++ks) vf[(d + 1) & 1][ks] = *(const LAS bf16x8*)(vb + (d + 1) * 32 * VROW + ks * 32);
;                 }
; #pragma unroll
;                 for (int ks = 0; ks < 4; ++ks) o[d] = __builtin_amdgcn_mfma_f32_32x32x16_bf16(vf[d & 1][ks], pf[ks], o[d], 0, 0, 0);
;                 __builtin_amdgcn_sched_barrier(0);
;             }
.Lq_top2:
	s_cmp_eq_u32 s3, 0
	s_cbranch_scc1 .Lq_gen2
	s_add_i32 s13, s3, 1
	s_cmp_ge_i32 s13, s20
	s_cbranch_scc1 .Lq_gen2
	ds_read_b128 v[96:99], v213 offset:22528
	ds_read_b128 v[104:107], v213 offset:29184
	ds_read_b128 v[100:103], v213 offset:22560
	ds_read_b128 v[108:111], v213 offset:29216
	v_mfma_f32_32x32x16_bf16 v[32:47], v[152:155], v[214:217], v[32:47]
	v_exp_f32_e32 v64, v64
	v_exp_f32_e32 v65, v65
	ds_read_b128 v[112:115], v213 offset:22592
	ds_read_b128 v[120:123], v213 offset:29248
	ds_read_b128 v[116:119], v213 offset:22624
	ds_read_b128 v[124:127], v213 offset:29280
	v_mfma_f32_32x32x16_bf16 v[16:31], v[188:191], v[214:217], v[16:31]
	v_exp_f32_e32 v80, v80
	v_exp_f32_e32 v81, v81
	v_add_f32_e32 v204, v64, v175
	s_waitcnt vmcnt(0)
	ds_write_b128 v14, v[140:143] offset:0
	v_mfma_f32_32x32x16_bf16 v[32:47], v[156:159], v[218:221], v[32:47]
	v_exp_f32_e32 v66, v66
	v_exp_f32_e32 v67, v67
	v_add_f32_e32 v204, v80, v204
	v_add_f32_e32 v205, v65, v81
	ds_write_b128 v174, v[148:151] offset:13312
	v_mfma_f32_32x32x16_bf16 v[16:31], v[192:195], v[218:221], v[16:31]
	v_exp_f32_e32 v82, v82
	v_exp_f32_e32 v83, v83
	v_add_f32_e32 v204, v66, v204
	v_add_f32_e32 v205, v67, v205
	s_and_saveexec_b64 s[14:15], s[10:11]
	ds_write_b128 v172, v[144:147] offset:0
	s_or_b64 exec, exec, s[14:15]
	v_mfma_f32_32x32x16_bf16 v[32:47], v[160:163], v[222:225], v[32:47]
	v_exp_f32_e32 v68, v68
	v_exp_f32_e32 v69, v69
	v_add_f32_e32 v204, v82, v204
	v_add_f32_e32 v205, v83, v205
	s_add_i32 s12, s3, 3
	s_cmp_ge_i32 s12, s2
	s_cbranch_scc1 .Lq_ng0_s2
	s_and_saveexec_b64 s[14:15], s[10:11]
	global_load_dwordx4 v[144:147], v180, s[98:99]
	s_or_b64 exec, exec, s[14:15]

; #define LAS __attribute__((address_space(3)))
; template <int DQK, int DV, int FLAGS, int qp, int kp, int vts, int op> ...
;     ...
; #pragma unroll
;             for (int c = 0; c < ND0 / 2; ++c) {
;                 if (c + 1 < ND0 / 2) {
; #pragma unroll
;                     for (int i = 0; i < 2; ++i) { kf[(c + 1) & 1][2 * i] = *(const LAS bf16x8*)(kb + (2 * c + 2 + i) * 32); kf[(c + 1) & 1][2 * i + 1] = *(const LAS bf16x8*)(kb + 32 * KROW + (2 * c + 2 + i) * 32); }
;                 }
; #pragma unroll
;                 for (int i = 0; i < 2; ++i) {
;                     p0 = __builtin_amdgcn_mfma_f32_32x32x16_bf16(kf[c & 1][2 * i], qr[2 * c + i], p0, 0, 0, 0);
;                     p1 = __builtin_amdgcn_mfma_f32_32x32x16_bf16(kf[c & 1][2 * i + 1], qr[2 * c + i], p1, 0, 0, 0);
;                 }
;                 __builtin_amdgcn_sched_barrier(0);
;             }
;             if (more) ATT_GLOAD((FLAGS & AF_REV) ? t - 1 : t + 1);
;             bf16x8 vf[2][4];
; #pragma unroll
;             for (int ks = 0; ks < 4; ++ks) vf[0][ks] = *(const LAS bf16x8*)(vb + ks * 32);
;     ...
;             f32x2 rs2 = {0.f, 0.f};
; #pragma unroll
;             for (int r = 0; r < 16; ++r) { p0[r] = __builtin_amdgcn_exp2f(p0[r]); p1[r] = __builtin_amdgcn_exp2f(p1[r]); }
; #pragma unroll
;             for (int r = 0; r < 16; r += 2) { rs2 += (f32x2){p0[r], p0[r + 1]}; rs2 += (f32x2){p1[r], p1[r + 1]}; }
;             l += rs2.x + rs2.y;
;             bf16x8 pf[4];
;             pf[0] = pack_bf16x8(p0, 0); pf[1] = pack_bf16x8(p0, 8); pf[2] = pack_bf16x8(p1, 0); pf[3] = pack_bf16x8(p1, 8);
;             __builtin_amdgcn_sched_barrier(0);
; #pragma unroll
;             for (int d = 0; d < NDB; ++d) {
;                 if (d + 1 < NDB) {
; #pragma unroll
;                     for (int ks = 0; ks < 4; ++ks) vf[(d + 1) & 1][ks] = *(const LAS bf16x8*)(vb + (d + 1) * 32 * VROW + ks * 32);
;                 }
; #pragma unroll
;                 for (int ks = 0; ks < 4; ++ks) o[d] = __builtin_amdgcn_mfma_f32_32x32x16_bf16(vf[d & 1][ks], pf[ks], o[d], 0, 0, 0);
;                 __builtin_amdgcn_sched_barrier(0);
;             }
.Lq_ng2_s2:
	v_mfma_f32_32x32x16_bf16 v[16:31], v[200:203], v[226:229], v[16:31]
	v_exp_f32_e32 v86, v86
	v_exp_f32_e32 v87, v87
	v_add_f32_e32 v204, v70, v204
	v_add_f32_e32 v205, v71, v205
	s_waitcnt lgkmcnt(6)
	v_mfma_f32_32x32x16_bf16 v[214:229], v[96:99], v[2:5], v[48:63]
	v_exp_f32_e32 v72, v72
	v_exp_f32_e32 v73, v73
	v_add_f32_e32 v204, v86, v204
	v_add_f32_e32 v205, v87, v205
	v_mfma_f32_32x32x16_bf16 v[230:245], v[104:107], v[2:5], v[48:63]
	v_exp_f32_e32 v88, v88
	v_exp_f32_e32 v89, v89
	v_add_f32_e32 v204, v72, v204
	v_add_f32_e32 v205, v73, v205
	v_mfma_f32_32x32x16_bf16 v[214:229], v[100:103], v[6:9], v[214:229]
	v_exp_f32_e32 v74, v74
	v_exp_f32_e32 v75, v75
	v_add_f32_e32 v204, v88, v204
	v_add_f32_e32 v205, v89, v205
	v_mfma_f32_32x32x16_bf16 v[230:245], v[108:111], v[6:9], v[230:245]
	v_exp_f32_e32 v90, v90
	v_exp_f32_e32 v91, v91
	v_add_f32_e32 v204, v74, v204
	v_add_f32_e32 v205, v75, v205
	ds_read_b128 v[96:99], v213 offset:22656
	ds_read_b128 v[104:107], v213 offset:29312
	ds_read_b128 v[100:103], v213 offset:22688
	ds_read_b128 v[108:111], v213 offset:29344
	s_waitcnt lgkmcnt(6)
	v_mfma_f32_32x32x16_bf16 v[214:229], v[112:115], v[10:13], v[214:229]
	v_exp_f32_e32 v76, v76
	v_exp_f32_e32 v77, v77
	v_add_f32_e32 v204, v90, v204
	v_add_f32_e32 v205, v91, v205
	v_mfma_f32_32x32x16_bf16 v[230:245], v[120:123], v[10:13], v[230:245]
	v_exp_f32_e32 v92, v92
	v_exp_f32_e32 v93, v93
	v_add_f32_e32 v204, v76, v204
	v_add_f32_e32 v205, v77, v205
	ds_read_b128 v[152:155], v247 offset:13312
	ds_read_b128 v[156:159], v247 offset:13344
	ds_read_b128 v[160:163], v247 offset:13376
	ds_read_b128 v[164:167], v247 offset:13408
	v_mfma_f32_32x32x16_bf16 v[214:229], v[116:119], v[128:131], v[214:229]
	v_exp_f32_e32 v78, v78
	v_exp_f32_e32 v79, v79
	v_add_f32_e32 v204, v92, v204
	v_add_f32_e32 v205, v93, v205
	v_mfma_f32_32x32x16_bf16 v[230:245], v[124:127], v[128:131], v[230:245]
	v_exp_f32_e32 v94, v94
	v_exp_f32_e32 v95, v95
	v_add_f32_e32 v204, v78, v204
	v_add_f32_e32 v205, v79, v205
	ds_read_b128 v[188:191], v247 offset:17920
	ds_read_b128 v[192:195], v247 offset:17952
	ds_read_b128 v[196:199], v247 offset:17984
	ds_read_b128 v[200:203], v247 offset:18016
	s_waitcnt lgkmcnt(8)
	v_mfma_f32_32x32x16_bf16 v[214:229], v[96:99], v[132:135], v[214:229]
	v_add_f32_e32 v204, v94, v204
	v_add_f32_e32 v205, v95, v205
	v_cvt_pk_bf16_f32 v64, v64, v65
	v_cvt_pk_bf16_f32 v65, v66, v67
	v_cvt_pk_bf16_f32 v66, v68, v69
	v_mfma_f32_32x32x16_bf16 v[230:245], v[104:107], v[132:135], v[230:245]
	v_cvt_pk_bf16_f32 v67, v70, v71
	v_cvt_pk_bf16_f32 v68, v72, v73
	v_cvt_pk_bf16_f32 v69, v74, v75
	v_cvt_pk_bf16_f32 v70, v76, v77
	v_cvt_pk_bf16_f32 v71, v78, v79
	v_mfma_f32_32x32x16_bf16 v[214:229], v[100:103], v[136:139], v[214:229]
	v_cvt_pk_bf16_f32 v72, v80, v81
	v_cvt_pk_bf16_f32 v73, v82, v83
	v_cvt_pk_bf16_f32 v74, v84, v85
	v_cvt_pk_bf16_f32 v75, v86, v87
	v_cvt_pk_bf16_f32 v76, v88, v89
	v_mfma_f32_32x32x16_bf16 v[230:245], v[108:111], v[136:139], v[230:245]
	v_cvt_pk_bf16_f32 v77, v90, v91
	v_cvt_pk_bf16_f32 v78, v92, v93
	v_cvt_pk_bf16_f32 v79, v94, v95
	v_add_f32_e32 v175, v204, v205
	s_branch .Lq_tailb2

; #define LAS __attribute__((address_space(3)))
; template <int DQK, int DV, int FLAGS, int qp, int kp, int vts, int op> ...
;     ...
; #pragma unroll
;             for (int c = 0; c < ND0 / 2; ++c) {
;                 if (c + 1 < ND0 / 2) {
; #pragma unroll
;                     for (int i = 0; i < 2; ++i) { kf[(c + 1) & 1][2 * i] = *(const LAS bf16x8*)(kb + (2 * c + 2 + i) * 32); kf[(c + 1) & 1][2 * i + 1] = *(const LAS bf16x8*)(kb + 32 * KROW + (2 * c + 2 + i) * 32); }
;                 }
; #pragma unroll
;                 for (int i = 0; i < 2; ++i) {
;                     p0 = __builtin_amdgcn_mfma_f32_32x32x16_bf16(kf[c & 1][2 * i], qr[2 * c + i], p0, 0, 0, 0);
;                     p1 = __builtin_amdgcn_mfma_f32_32x32x16_bf16(kf[c & 1][2 * i + 1], qr[2 * c + i], p1, 0, 0, 0);
;                 }
;                 __builtin_amdgcn_sched_barrier(0);
;             }
;             if (more) ATT_GLOAD((FLAGS & AF_REV) ? t - 1 : t + 1);
;             bf16x8 vf[2][4];
; #pragma unroll
;             for (int ks = 0; ks < 4; ++ks) vf[0][ks] = *(const LAS bf16x8*)(vb + ks * 32);
;     ...
;             f32x2 rs2 = {0.f, 0.f};
; #pragma unroll
;             for (int r = 0; r < 16; ++r) { p0[r] = __builtin_amdgcn_exp2f(p0[r]); p1[r] = __builtin_amdgcn_exp2f(p1[r]); }
; #pragma unroll
;             for (int r = 0; r < 16; r += 2) { rs2 += (f32x2){p0[r], p0[r + 1]}; rs2 += (f32x2){p1[r], p1[r + 1]}; }
;             l += rs2.x + rs2.y;
;             bf16x8 pf[4];
;             pf[0] = pack_bf16x8(p0, 0); pf[1] = pack_bf16x8(p0, 8); pf[2] = pack_bf16x8(p1, 0); pf[3] = pack_bf16x8(p1, 8);
;             __builtin_amdgcn_sched_barrier(0);
; #pragma unroll
;             for (int d = 0; d < NDB; ++d) {
;                 if (d + 1 < NDB) {
; #pragma unroll
;                     for (int ks = 0; ks < 4; ++ks) vf[(d + 1) & 1][ks] = *(const LAS bf16x8*)(vb + (d + 1) * 32 * VROW + ks * 32);
;                 }
; #pragma unroll
;                 for (int ks = 0; ks < 4; ++ks) o[d] = __builtin_amdgcn_mfma_f32_32x32x16_bf16(vf[d & 1][ks], pf[ks], o[d], 0, 0, 0);
;                 __builtin_amdgcn_sched_barrier(0);
;             }
.Lq_top3:
	s_cmp_eq_u32 s3, 0
	s_cbranch_scc1 .Lq_gen3
	s_add_i32 s13, s3, 1
	s_cmp_ge_i32 s13, s20
	s_cbranch_scc1 .Lq_gen3
	ds_read_b128 v[96:99], v187 offset:0
	ds_read_b128 v[104:107], v187 offset:6656
	ds_read_b128 v[100:103], v187 offset:32
	ds_read_b128 v[108:111], v187 offset:6688
	v_mfma_f32_32x32x16_bf16 v[32:47], v[152:155], v[64:67], v[32:47]
	v_exp_f32_e32 v214, v214
	v_exp_f32_e32 v215, v215
	ds_read_b128 v[112:115], v187 offset:64
	ds_read_b128 v[120:123], v187 offset:6720
	ds_read_b128 v[116:119], v187 offset:96
	ds_read_b128 v[124:127], v187 offset:6752
	v_mfma_f32_32x32x16_bf16 v[16:31], v[188:191], v[64:67], v[16:31]
	v_exp_f32_e32 v230, v230
	v_exp_f32_e32 v231, v231
	v_add_f32_e32 v204, v214, v175
	s_waitcnt vmcnt(0)
	ds_write_b128 v14, v[140:143] offset:22528
	v_mfma_f32_32x32x16_bf16 v[32:47], v[156:159], v[68:71], v[32:47]
	v_exp_f32_e32 v216, v216
	v_exp_f32_e32 v217, v217
	v_add_f32_e32 v204, v230, v204
	v_add_f32_e32 v205, v215, v231
	ds_write_b128 v174, v[148:151] offset:35840
	v_mfma_f32_32x32x16_bf16 v[16:31], v[192:195], v[68:71], v[16:31]
	v_exp_f32_e32 v232, v232
	v_exp_f32_e32 v233, v233
	v_add_f32_e32 v204, v216, v204
	v_add_f32_e32 v205, v217, v205
	s_and_saveexec_b64 s[14:15], s[10:11]
	ds_write_b128 v172, v[144:147] offset:22528
	s_or_b64 exec, exec, s[14:15]
	v_mfma_f32_32x32x16_bf16 v[32:47], v[160:163], v[72:75], v[32:47]
	v_exp_f32_e32 v218, v218
	v_exp_f32_e32 v219, v219
	v_add_f32_e32 v204, v232, v204
	v_add_f32_e32 v205, v233, v205
	s_add_i32 s12, s3, 3
	s_cmp_ge_i32 s12, s2
	s_cbranch_scc1 .Lq_ng0_s3
	s_and_saveexec_b64 s[14:15], s[10:11]
	global_load_dwordx4 v[144:147], v180, s[98:99]
	s_or_b64 exec, exec, s[14:15]

; #define LAS __attribute__((address_space(3)))
; template <int DQK, int DV, int FLAGS, int qp, int kp, int vts, int op> ...
;     ...
; #pragma unroll
;             for (int c = 0; c < ND0 / 2; ++c) {
;                 if (c + 1 < ND0 / 2) {
; #pragma unroll
;                     for (int i = 0; i < 2; ++i) { kf[(c + 1) & 1][2 * i] = *(const LAS bf16x8*)(kb + (2 * c + 2 + i) * 32); kf[(c + 1) & 1][2 * i + 1] = *(const LAS bf16x8*)(kb + 32 * KROW + (2 * c + 2 + i) * 32); }
;                 }
; #pragma unroll
;                 for (int i = 0; i < 2; ++i) {
;                     p0 = __builtin_amdgcn_mfma_f32_32x32x16_bf16(kf[c & 1][2 * i], qr[2 * c + i], p0, 0, 0, 0);
;                     p1 = __builtin_amdgcn_mfma_f32_32x32x16_bf16(kf[c & 1][2 * i + 1], qr[2 * c + i], p1, 0, 0, 0);
;                 }
;                 __builtin_amdgcn_sched_barrier(0);
;             }
;             if (more) ATT_GLOAD((FLAGS & AF_REV) ? t - 1 : t + 1);
;             bf16x8 vf[2][4];
; #pragma unroll
;             for (int ks = 0; ks < 4; ++ks) vf[0][ks] = *(const LAS bf16x8*)(vb + ks * 32);
;     ...
;             f32x2 rs2 = {0.f, 0.f};
; #pragma unroll
;             for (int r = 0; r < 16; ++r) { p0[r] = __builtin_amdgcn_exp2f(p0[r]); p1[r] = __builtin_amdgcn_exp2f(p1[r]); }
; #pragma unroll
;             for (int r = 0; r < 16; r += 2) { rs2 += (f32x2){p0[r], p0[r + 1]}; rs2 += (f32x2){p1[r], p1[r + 1]}; }
;             l += rs2.x + rs2.y;
;             bf16x8 pf[4];
;             pf[0] = pack_bf16x8(p0, 0); pf[1] = pack_bf16x8(p0, 8); pf[2] = pack_bf16x8(p1, 0); pf[3] = pack_bf16x8(p1, 8);
;             __builtin_amdgcn_sched_barrier(0);
; #pragma unroll
;             for (int d = 0; d < NDB; ++d) {
;                 if (d + 1 < NDB) {
; #pragma unroll
;                     for (int ks = 0; ks < 4; ++ks) vf[(d + 1) & 1][ks] = *(const LAS bf16x8*)(vb + (d + 1) * 32 * VROW + ks * 32);
;                 }
; #pragma unroll
;                 for (int ks = 0; ks < 4; ++ks) o[d] = __builtin_amdgcn_mfma_f32_32x32x16_bf16(vf[d & 1][ks], pf[ks], o[d], 0, 0, 0);
;                 __builtin_amdgcn_sched_barrier(0);
;             }
.Lq_ng2_s3:
	v_mfma_f32_32x32x16_bf16 v[16:31], v[200:203], v[76:79], v[16:31]
	v_exp_f32_e32 v236, v236
	v_exp_f32_e32 v237, v237
	v_add_f32_e32 v204, v220, v204
	v_add_f32_e32 v205, v221, v205
	s_waitcnt lgkmcnt(6)
	v_mfma_f32_32x32x16_bf16 v[64:79], v[96:99], v[2:5], v[48:63]
	v_exp_f32_e32 v222, v222
	v_exp_f32_e32 v223, v223
	v_add_f32_e32 v204, v236, v204
	v_add_f32_e32 v205, v237, v205
	v_mfma_f32_32x32x16_bf16 v[80:95], v[104:107], v[2:5], v[48:63]
	v_exp_f32_e32 v238, v238
	v_exp_f32_e32 v239, v239
	v_add_f32_e32 v204, v222, v204
	v_add_f32_e32 v205, v223, v205
	v_mfma_f32_32x32x16_bf16 v[64:79], v[100:103], v[6:9], v[64:79]
	v_exp_f32_e32 v224, v224
	v_exp_f32_e32 v225, v225
	v_add_f32_e32 v204, v238, v204
	v_add_f32_e32 v205, v239, v205
	v_mfma_f32_32x32x16_bf16 v[80:95], v[108:111], v[6:9], v[80:95]
	v_exp_f32_e32 v240, v240
	v_exp_f32_e32 v241, v241
	v_add_f32_e32 v204, v224, v204
	v_add_f32_e32 v205, v225, v205
	ds_read_b128 v[96:99], v187 offset:128
	ds_read_b128 v[104:107], v187 offset:6784
	ds_read_b128 v[100:103], v187 offset:160
	ds_read_b128 v[108:111], v187 offset:6816
	s_waitcnt lgkmcnt(6)
	v_mfma_f32_32x32x16_bf16 v[64:79], v[112:115], v[10:13], v[64:79]
	v_exp_f32_e32 v226, v226
	v_exp_f32_e32 v227, v227
	v_add_f32_e32 v204, v240, v204
	v_add_f32_e32 v205, v241, v205
	v_mfma_f32_32x32x16_bf16 v[80:95], v[120:123], v[10:13], v[80:95]
	v_exp_f32_e32 v242, v242
	v_exp_f32_e32 v243, v243
	v_add_f32_e32 v204, v226, v204
	v_add_f32_e32 v205, v227, v205
	ds_read_b128 v[152:155], v247 offset:35840
	ds_read_b128 v[156:159], v247 offset:35872
	ds_read_b128 v[160:163], v247 offset:35904
	ds_read_b128 v[164:167], v247 offset:35936
	v_mfma_f32_32x32x16_bf16 v[64:79], v[116:119], v[128:131], v[64:79]
	v_exp_f32_e32 v228, v228
	v_exp_f32_e32 v229, v229
	v_add_f32_e32 v204, v242, v204
	v_add_f32_e32 v205, v243, v205
	v_mfma_f32_32x32x16_bf16 v[80:95], v[124:127], v[128:131], v[80:95]
	v_exp_f32_e32 v244, v244
	v_exp_f32_e32 v245, v245
	v_add_f32_e32 v204, v228, v204
	v_add_f32_e32 v205, v229, v205
	ds_read_b128 v[188:191], v247 offset:40448
	ds_read_b128 v[192:195], v247 offset:40480
	ds_read_b128 v[196:199], v247 offset:40512
	ds_read_b128 v[200:203], v247 offset:40544
	s_waitcnt lgkmcnt(8)
	v_mfma_f32_32x32x16_bf16 v[64:79], v[96:99], v[132:135], v[64:79]
	v_add_f32_e32 v204, v244, v204
	v_add_f32_e32 v205, v245, v205
	v_cvt_pk_bf16_f32 v214, v214, v215
	v_cvt_pk_bf16_f32 v215, v216, v217
	v_cvt_pk_bf16_f32 v216, v218, v219
	v_mfma_f32_32x32x16_bf16 v[80:95], v[104:107], v[132:135], v[80:95]
	v_cvt_pk_bf16_f32 v217, v220, v221
	v_cvt_pk_bf16_f32 v218, v222, v223
	v_cvt_pk_bf16_f32 v219, v224, v225
	v_cvt_pk_bf16_f32 v220, v226, v227
	v_cvt_pk_bf16_f32 v221, v228, v229
	v_mfma_f32_32x32x16_bf16 v[64:79], v[100:103], v[136:139], v[64:79]
	v_cvt_pk_bf16_f32 v222, v230, v231
	v_cvt_pk_bf16_f32 v223, v232, v233
	v_cvt_pk_bf16_f32 v224, v234, v235
	v_cvt_pk_bf16_f32 v225, v236, v237
	v_cvt_pk_bf16_f32 v226, v238, v239
	v_mfma_f32_32x32x16_bf16 v[80:95], v[108:111], v[136:139], v[80:95]
	v_cvt_pk_bf16_f32 v227, v240, v241
	v_cvt_pk_bf16_f32 v228, v242, v243
	v_cvt_pk_bf16_f32 v229, v244, v245
	v_add_f32_e32 v175, v204, v205
	s_branch .Lq_tailb3
